# flat release: non-leader workgroups poll the cross-XCD TOPGEN word instead of their XCD's XGEN (one hop fewer per grid barrier)
# speedup vs baseline: 1.0025x; 1.0025x over previous
.LBB0_60:
	s_or_b64 exec, exec, s[10:11]
	s_cmp_eq_u32 s3, 0
	s_cselect_b64 vcc, -1, 0
	s_cmp_eq_u32 s3, 1
	v_cndmask_b32_e32 v18, 0, v15, vcc
	s_cselect_b64 vcc, -1, 0
	s_cmp_eq_u32 s3, 2
	v_cndmask_b32_e32 v18, v18, v3, vcc
	s_cselect_b64 vcc, -1, 0
	s_cmp_eq_u32 s3, 3
	v_cndmask_b32_e32 v18, v18, v4, vcc
	s_cselect_b64 vcc, -1, 0
	s_cmp_eq_u32 s3, 4
	v_cndmask_b32_e32 v18, v18, v5, vcc
	s_cselect_b64 vcc, -1, 0
	s_cmp_eq_u32 s3, 5
	v_cndmask_b32_e32 v18, v18, v6, vcc
	s_cselect_b64 vcc, -1, 0
	s_cmp_eq_u32 s3, 6
	v_cndmask_b32_e32 v18, v18, v7, vcc
	s_cselect_b64 vcc, -1, 0
	s_cmp_eq_u32 s3, 7
	v_cndmask_b32_e32 v18, v18, v8, vcc
	s_cselect_b64 vcc, -1, 0
	s_cmp_eq_u32 s3, 8
	v_cndmask_b32_e32 v18, v18, v9, vcc
	s_cselect_b64 vcc, -1, 0
	s_cmp_eq_u32 s3, 9
	v_cndmask_b32_e32 v18, v18, v10, vcc
	s_cselect_b64 vcc, -1, 0
	s_cmp_eq_u32 s3, 10
	v_cndmask_b32_e32 v18, v18, v11, vcc
	s_cselect_b64 vcc, -1, 0
	s_cmp_eq_u32 s3, 11
	v_cndmask_b32_e32 v18, v18, v12, vcc
	s_cselect_b64 vcc, -1, 0
	s_cmp_eq_u32 s3, 12
	v_cndmask_b32_e32 v18, v18, v13, vcc
	s_cselect_b64 vcc, -1, 0
	s_cmp_eq_u32 s3, 13
	v_cndmask_b32_e32 v18, v18, v14, vcc
	s_cselect_b64 vcc, -1, 0
	s_cmp_eq_u32 s3, 14
	v_cndmask_b32_e32 v18, v18, v1, vcc
	s_cselect_b64 vcc, -1, 0
	s_cmp_eq_u32 s3, 15
	v_cndmask_b32_e32 v18, v18, v2, vcc
	s_cselect_b64 vcc, -1, 0
	v_cndmask_b32_e32 v18, v18, v0, vcc
	v_cmp_ne_u32_e32 vcc, 0, v15
	v_max_u32_e32 v180, 1, v18
	s_waitcnt vmcnt(0)
	v_readfirstlane_b32 s8, v17
	v_cndmask_b32_e64 v15, 0, 1, vcc
	v_cmp_ne_u32_e32 vcc, 0, v3
	s_nop 1
	v_addc_co_u32_e32 v3, vcc, 0, v15, vcc
	v_cmp_ne_u32_e32 vcc, 0, v4
	s_nop 1
	v_cndmask_b32_e64 v4, 0, 1, vcc
	v_cmp_ne_u32_e32 vcc, 0, v5
	v_cvt_f32_u32_e32 v5, v180
	s_nop 0
	v_addc_co_u32_e32 v3, vcc, v3, v4, vcc
	v_cmp_ne_u32_e32 vcc, 0, v6
	s_nop 1
	v_cndmask_b32_e64 v4, 0, 1, vcc
	v_cmp_ne_u32_e32 vcc, 0, v7
	s_nop 1
	v_addc_co_u32_e32 v3, vcc, v3, v4, vcc
	v_cmp_ne_u32_e32 vcc, 0, v8
	s_nop 1
	v_cndmask_b32_e64 v4, 0, 1, vcc
	v_cmp_ne_u32_e32 vcc, 0, v9
	s_nop 1
	v_addc_co_u32_e32 v3, vcc, v3, v4, vcc
	v_cmp_ne_u32_e32 vcc, 0, v10
	s_nop 1
	v_cndmask_b32_e64 v4, 0, 1, vcc
	v_cmp_ne_u32_e32 vcc, 0, v11
	s_nop 1
	v_addc_co_u32_e32 v3, vcc, v3, v4, vcc
	v_cmp_ne_u32_e32 vcc, 0, v12
	s_nop 1
	v_cndmask_b32_e64 v4, 0, 1, vcc
	v_cmp_ne_u32_e32 vcc, 0, v13
	s_nop 1
	v_addc_co_u32_e32 v3, vcc, v3, v4, vcc
	v_cmp_ne_u32_e32 vcc, 0, v14
	s_nop 1
	v_cndmask_b32_e64 v4, 0, 1, vcc
	v_cmp_ne_u32_e32 vcc, 0, v1
	s_nop 1
	v_addc_co_u32_e32 v1, vcc, v3, v4, vcc
	v_rcp_iflag_f32_e32 v3, v5
	v_cmp_ne_u32_e32 vcc, 0, v2
	s_nop 1
	v_cndmask_b32_e64 v2, 0, 1, vcc
	v_cmp_ne_u32_e32 vcc, 0, v0
	s_nop 1
	v_addc_co_u32_e32 v0, vcc, v1, v2, vcc
	v_mul_f32_e32 v1, 0x4f7ffffe, v3
	v_cvt_u32_f32_e32 v1, v1
	v_sub_u32_e32 v3, 0, v180
	v_add_u32_e32 v2, s8, v16
	v_mul_lo_u32 v3, v3, v1
	v_mul_hi_u32 v3, v1, v3
	v_add_u32_e32 v1, v1, v3
	v_mul_hi_u32 v1, v2, v1
	v_mul_lo_u32 v3, v1, v180
	v_sub_u32_e32 v3, v2, v3
	v_add_u32_e32 v4, 1, v1
	v_cmp_ge_u32_e32 vcc, v3, v180
	v_add_u32_e32 v2, 1, v2
	s_nop 0
	v_cndmask_b32_e32 v1, v1, v4, vcc
	v_sub_u32_e32 v4, v3, v180
	v_cndmask_b32_e32 v3, v3, v4, vcc
	v_add_u32_e32 v4, 1, v1
	v_cmp_ge_u32_e32 vcc, v3, v180
	s_nop 1
	v_cndmask_b32_e32 v1, v1, v4, vcc
	v_mul_lo_u32 v3, v180, v1
	v_add_u32_e32 v3, v3, v180
	v_cmp_ne_u32_e32 vcc, v2, v3
	s_and_saveexec_b64 s[8:9], vcc
	s_xor_b64 s[8:9], exec, s[8:9]
	s_cbranch_execz .LBB0_74
	v_mov_b32_e32 v2, 0x3100
	global_load_dword v2, v2, s[26:27] offset:1024 sc1
	s_add_u32 s12, s26, 0x3500
	s_addc_u32 s13, s27, 0
	s_waitcnt vmcnt(0)
	v_cmp_eq_u32_e32 vcc, v2, v1
	s_and_saveexec_b64 s[10:11], vcc
	s_cbranch_execz .LBB0_73
	s_mov_b32 s33, 1
	s_mov_b64 s[14:15], 0
	v_mov_b32_e32 v2, 0
	s_branch .LBB0_64

.LBB0_429:
	s_or_b64 exec, exec, s[8:9]
	v_cvt_f32_u32_e32 v2, v180
	s_waitcnt vmcnt(0)
	v_readfirstlane_b32 s6, v1
	v_rcp_iflag_f32_e32 v2, v2
	s_nop 0
	v_add_u32_e32 v0, s6, v0
	v_add_u32_e32 v4, 1, v0
	v_mul_f32_e32 v1, 0x4f7ffffe, v2
	v_cvt_u32_f32_e32 v1, v1
	v_sub_u32_e32 v2, 0, v180
	v_mul_lo_u32 v2, v2, v1
	v_mul_hi_u32 v2, v1, v2
	v_add_u32_e32 v1, v1, v2
	v_mul_hi_u32 v1, v0, v1
	v_mul_lo_u32 v2, v1, v180
	v_sub_u32_e32 v0, v0, v2
	v_add_u32_e32 v3, 1, v1
	v_cmp_ge_u32_e32 vcc, v0, v180
	v_sub_u32_e32 v2, v0, v180
	s_nop 0
	v_cndmask_b32_e32 v1, v1, v3, vcc
	v_cndmask_b32_e32 v0, v0, v2, vcc
	v_add_u32_e32 v2, 1, v1
	v_cmp_ge_u32_e32 vcc, v0, v180
	s_nop 1
	v_cndmask_b32_e32 v0, v1, v2, vcc
	v_mad_u64_u32 v[2:3], s[6:7], v180, v0, v[180:181]
	v_cmp_ne_u32_e32 vcc, v4, v2
	s_and_saveexec_b64 s[6:7], vcc
	s_xor_b64 s[6:7], exec, s[6:7]
	s_cbranch_execz .LBB0_443
	v_mov_b32_e32 v1, 0x3100
	global_load_dword v1, v1, s[26:27] offset:1024 sc1
	s_add_u32 s12, s26, 0x3500
	s_addc_u32 s13, s27, 0
	s_waitcnt vmcnt(0)
	v_cmp_eq_u32_e32 vcc, v1, v0
	s_and_saveexec_b64 s[8:9], vcc
	s_cbranch_execz .LBB0_442
	s_add_u32 s10, s20, 0x1d750200
	s_addc_u32 s11, s21, 0
	s_mov_b32 s29, 1
	s_mov_b64 s[14:15], 0
	v_mov_b32_e32 v1, 0
	s_branch .LBB0_433

.LBB0_1186:
	s_or_b64 exec, exec, s[10:11]
	v_cvt_f32_u32_e32 v2, v180
	s_waitcnt vmcnt(0)
	v_readfirstlane_b32 s3, v1
	v_rcp_iflag_f32_e32 v2, v2
	s_nop 0
	v_add_u32_e32 v0, s3, v0
	v_add_u32_e32 v4, 1, v0
	v_mul_f32_e32 v1, 0x4f7ffffe, v2
	v_cvt_u32_f32_e32 v1, v1
	v_sub_u32_e32 v2, 0, v180
	v_mul_lo_u32 v2, v2, v1
	v_mul_hi_u32 v2, v1, v2
	v_add_u32_e32 v1, v1, v2
	v_mul_hi_u32 v1, v0, v1
	v_mul_lo_u32 v2, v1, v180
	v_sub_u32_e32 v0, v0, v2
	v_add_u32_e32 v3, 1, v1
	v_cmp_ge_u32_e32 vcc, v0, v180
	v_sub_u32_e32 v2, v0, v180
	s_nop 0
	v_cndmask_b32_e32 v1, v1, v3, vcc
	v_cndmask_b32_e32 v0, v0, v2, vcc
	v_add_u32_e32 v2, 1, v1
	v_cmp_ge_u32_e32 vcc, v0, v180
	s_nop 1
	v_cndmask_b32_e32 v0, v1, v2, vcc
	v_mad_u64_u32 v[2:3], s[8:9], v180, v0, v[180:181]
	v_cmp_ne_u32_e32 vcc, v4, v2
	s_and_saveexec_b64 s[8:9], vcc
	s_xor_b64 s[8:9], exec, s[8:9]
	s_cbranch_execz .LBB0_1200
	v_mov_b32_e32 v1, 0x3100
	global_load_dword v1, v1, s[26:27] offset:1024 sc1
	s_add_u32 s14, s26, 0x3500
	s_addc_u32 s15, s27, 0
	s_waitcnt vmcnt(0)
	v_cmp_eq_u32_e32 vcc, v1, v0
	s_and_saveexec_b64 s[10:11], vcc
	s_cbranch_execz .LBB0_1199
	s_add_u32 s12, s20, 0x1d750200
	s_addc_u32 s13, s21, 0
	s_mov_b32 s3, 1
	s_mov_b64 s[16:17], 0
	v_mov_b32_e32 v1, 0
	s_branch .LBB0_1190
